# v27 + static s_setprio 1 at entry for waves 4-7 (younger wave per SIMD)
# baseline (speedup 1.0000x reference)
_Z11mega_kernel6Params:
	s_mov_b32 s88, s2
	s_load_dwordx2 s[2:3], s[0:1], 0x80
	s_add_u32 s8, s0, 0x98
	v_and_b32_e32 v2, 0x3ff, v0
	s_addc_u32 s9, s1, 0
	v_readfirstlane_b32 s14, v2
	s_waitcnt lgkmcnt(0)
	v_writelane_b32 v254, s2, 0
	s_cmp_lt_u32 s14, 0x100
	s_cbranch_scc1 .Lprio_lo
	s_setprio 1
.Lprio_lo:
	v_cmp_gt_u32_e32 vcc, 4, v2
	s_nop 0
	v_writelane_b32 v254, s3, 1
	s_and_saveexec_b64 s[2:3], vcc
	v_mov_b32_e32 v1, 0x24000
	v_lshl_or_b32 v1, v2, 2, v1
	v_mov_b32_e32 v3, 0
	ds_write_b32 v1, v3
	s_or_b64 exec, exec, s[2:3]
	s_load_dwordx2 s[90:91], s[0:1], 0x98
	s_cmp_lt_u32 s14, 64
	s_mov_b64 s[6:7], 0
	s_cselect_b64 s[4:5], -1, 0
	s_cmp_gt_u32 s14, 63
	v_mbcnt_lo_u32_b32 v1, -1, 0
	s_waitcnt lgkmcnt(0)
	s_barrier
	s_cbranch_scc1 .LBB0_4
	v_mbcnt_hi_u32_b32 v3, -1, v1
	v_cmp_eq_u32_e32 vcc, 0, v3
	s_and_b64 s[6:7], vcc, exec
